# stack + FFN-down fused LN epilogue: 27 per-block vmcnt waits (store acks only) replaced by one up-front wait
# speedup vs baseline: 1.0065x; 1.0065x over previous
.LBB0_382:
	v_lshl_add_u32 v0, v196, 3, 0
	ds_read_b64 v[206:207], v0 offset:8192
	s_lshl_b64 s[8:9], s[24:25], 12
	s_add_u32 s20, s20, s8
	s_addc_u32 s21, s21, s9
	s_sub_u32 s2, 0, s26
	s_subb_u32 s8, 0, s27
	s_waitcnt lgkmcnt(0)
	v_sub_f32_e32 v143, v143, v206
	v_sub_f32_e32 v142, v142, v206
	v_sub_f32_e32 v145, v145, v206
	v_sub_f32_e32 v144, v144, v206
	s_add_u32 s10, s20, s2
	v_lshlrev_b64 v[196:197], 10, v[196:197]
	v_pk_mul_f32 v[144:145], v[206:207], v[144:145] op_sel:[1,0]
	v_pk_mul_f32 v[142:143], v[206:207], v[142:143] op_sel:[1,0]
	s_addc_u32 s11, s21, s8
	v_lshl_add_u64 v[196:197], v[196:197], 0, v[180:181]
	s_waitcnt vmcnt(0)
	v_pk_fma_f32 v[142:143], v[158:159], v[142:143], v[162:163]
	v_pk_fma_f32 v[144:145], v[160:161], v[144:145], v[164:165]
	v_cmp_eq_u32_e64 s[8:9], 0, v208
	s_mov_b64 s[22:23], -1
	s_and_b64 vcc, exec, s[4:5]
	v_cndmask_b32_e64 v145, v250, v145, s[8:9]
	v_cndmask_b32_e64 v144, v250, v144, s[8:9]
	v_cndmask_b32_e64 v143, v250, v143, s[8:9]
	v_cndmask_b32_e64 v142, v250, v142, s[8:9]
	v_lshl_add_u64 v[208:209], v[196:197], 2, s[20:21]
	s_cbranch_vccnz .LBB0_384
	s_mov_b64 s[22:23], 0
	global_store_dwordx4 v[208:209], v[142:145], off

.LBB0_386:
	s_lshl_b64 s[12:13], s[24:25], 10
	s_lshl_b64 s[12:13], s[12:13], 1
	s_add_u32 s2, s18, s12
	s_addc_u32 s12, s19, s13
	s_add_u32 s18, s2, 0x9a00000
	s_addc_u32 s19, s12, 0
	s_and_b64 vcc, exec, s[6:7]
	v_lshl_add_u64 v[196:197], v[196:197], 1, s[18:19]
	s_cbranch_vccnz .LBB0_388
	v_pk_fma_f32 v[142:143], v[214:215], v[142:143], v[174:175]
	v_pk_fma_f32 v[144:145], v[216:217], v[144:145], v[176:177]
	v_cvt_pk_bf16_f32 v142, v142, v143
	s_nop 0
	v_cvt_pk_bf16_f32 v143, v144, v145
	global_store_dwordx2 v[196:197], v[142:143], off

.LBB0_391:
	v_pk_fma_f32 v[138:139], v[214:215], v[138:139], v[174:175]
	v_pk_fma_f32 v[140:141], v[216:217], v[140:141], v[176:177]
	v_cvt_pk_bf16_f32 v138, v138, v139
	s_nop 0
	v_cvt_pk_bf16_f32 v139, v140, v141
	global_store_dwordx2 v[142:143], v[138:139], off

.LBB0_395:
	v_pk_fma_f32 v[134:135], v[214:215], v[134:135], v[174:175]
	v_pk_fma_f32 v[136:137], v[216:217], v[136:137], v[176:177]
	v_cvt_pk_bf16_f32 v134, v134, v135
	s_nop 0
	v_cvt_pk_bf16_f32 v135, v136, v137
	global_store_dwordx2 v[138:139], v[134:135], off

.LBB0_399:
	v_pk_fma_f32 v[130:131], v[214:215], v[130:131], v[174:175]
	v_pk_fma_f32 v[132:133], v[216:217], v[132:133], v[176:177]
	v_cvt_pk_bf16_f32 v130, v130, v131
	s_nop 0
	v_cvt_pk_bf16_f32 v131, v132, v133
	global_store_dwordx2 v[134:135], v[130:131], off

.LBB0_403:
	v_pk_fma_f32 v[126:127], v[214:215], v[126:127], v[174:175]
	v_pk_fma_f32 v[128:129], v[216:217], v[128:129], v[176:177]
	v_cvt_pk_bf16_f32 v126, v126, v127
	s_nop 0
	v_cvt_pk_bf16_f32 v127, v128, v129
	global_store_dwordx2 v[130:131], v[126:127], off

.LBB0_407:
	v_pk_fma_f32 v[122:123], v[214:215], v[122:123], v[174:175]
	v_pk_fma_f32 v[124:125], v[216:217], v[124:125], v[176:177]
	v_cvt_pk_bf16_f32 v122, v122, v123
	s_nop 0
	v_cvt_pk_bf16_f32 v123, v124, v125
	global_store_dwordx2 v[126:127], v[122:123], off

.LBB0_411:
	v_pk_fma_f32 v[118:119], v[214:215], v[118:119], v[174:175]
	v_pk_fma_f32 v[120:121], v[216:217], v[120:121], v[176:177]
	v_cvt_pk_bf16_f32 v118, v118, v119
	s_nop 0
	v_cvt_pk_bf16_f32 v119, v120, v121
	global_store_dwordx2 v[122:123], v[118:119], off

.LBB0_415:
	v_pk_fma_f32 v[114:115], v[214:215], v[114:115], v[174:175]
	v_pk_fma_f32 v[116:117], v[216:217], v[116:117], v[176:177]
	v_cvt_pk_bf16_f32 v114, v114, v115
	s_nop 0
	v_cvt_pk_bf16_f32 v115, v116, v117
	global_store_dwordx2 v[118:119], v[114:115], off
.LBB0_416:
	ds_read_b64 v[114:115], v0 offset:8192
	s_and_b64 vcc, exec, s[4:5]
	s_mov_b64 s[10:11], -1
	s_waitcnt lgkmcnt(0)
	v_sub_f32_e32 v111, v111, v114
	v_sub_f32_e32 v110, v110, v114
	v_sub_f32_e32 v113, v113, v114
	v_sub_f32_e32 v112, v112, v114
	v_pk_mul_f32 v[112:113], v[114:115], v[112:113] op_sel:[1,0]
	v_pk_mul_f32 v[110:111], v[114:115], v[110:111] op_sel:[1,0]
	v_pk_fma_f32 v[112:113], v[148:149], v[112:113], v[152:153]
	v_pk_fma_f32 v[110:111], v[146:147], v[110:111], v[150:151]
	v_cndmask_b32_e64 v113, v250, v113, s[8:9]
	v_cndmask_b32_e64 v112, v250, v112, s[8:9]
	v_cndmask_b32_e64 v111, v250, v111, s[8:9]
	v_cndmask_b32_e64 v110, v250, v110, s[8:9]
	s_cbranch_vccz .LBB0_542
	s_andn2_b64 vcc, exec, s[10:11]
	s_cbranch_vccz .LBB0_543

.LBB0_419:
	v_pk_fma_f32 v[110:111], v[210:211], v[110:111], v[170:171]
	v_pk_fma_f32 v[112:113], v[212:213], v[112:113], v[172:173]
	v_cvt_pk_bf16_f32 v110, v110, v111
	s_nop 0
	v_cvt_pk_bf16_f32 v111, v112, v113
	global_store_dwordx2 v[196:197], v[110:111], off offset:32

.LBB0_423:
	v_pk_fma_f32 v[106:107], v[210:211], v[106:107], v[170:171]
	v_pk_fma_f32 v[108:109], v[212:213], v[108:109], v[172:173]
	v_cvt_pk_bf16_f32 v106, v106, v107
	s_nop 0
	v_cvt_pk_bf16_f32 v107, v108, v109
	global_store_dwordx2 v[142:143], v[106:107], off offset:32

.LBB0_427:
	v_pk_fma_f32 v[102:103], v[210:211], v[102:103], v[170:171]
	v_pk_fma_f32 v[104:105], v[212:213], v[104:105], v[172:173]
	v_cvt_pk_bf16_f32 v102, v102, v103
	s_nop 0
	v_cvt_pk_bf16_f32 v103, v104, v105
	global_store_dwordx2 v[138:139], v[102:103], off offset:32

.LBB0_431:
	v_pk_fma_f32 v[98:99], v[210:211], v[98:99], v[170:171]
	v_pk_fma_f32 v[100:101], v[212:213], v[100:101], v[172:173]
	v_cvt_pk_bf16_f32 v98, v98, v99
	s_nop 0
	v_cvt_pk_bf16_f32 v99, v100, v101
	global_store_dwordx2 v[134:135], v[98:99], off offset:32

.LBB0_435:
	v_pk_fma_f32 v[94:95], v[210:211], v[94:95], v[170:171]
	v_pk_fma_f32 v[96:97], v[212:213], v[96:97], v[172:173]
	v_cvt_pk_bf16_f32 v94, v94, v95
	s_nop 0
	v_cvt_pk_bf16_f32 v95, v96, v97
	global_store_dwordx2 v[130:131], v[94:95], off offset:32

.LBB0_439:
	v_pk_fma_f32 v[90:91], v[210:211], v[90:91], v[170:171]
	v_pk_fma_f32 v[92:93], v[212:213], v[92:93], v[172:173]
	v_cvt_pk_bf16_f32 v90, v90, v91
	s_nop 0
	v_cvt_pk_bf16_f32 v91, v92, v93
	global_store_dwordx2 v[126:127], v[90:91], off offset:32

.LBB0_443:
	v_pk_fma_f32 v[78:79], v[210:211], v[78:79], v[170:171]
	v_pk_fma_f32 v[80:81], v[212:213], v[80:81], v[172:173]
	v_cvt_pk_bf16_f32 v78, v78, v79
	s_nop 0
	v_cvt_pk_bf16_f32 v79, v80, v81
	global_store_dwordx2 v[122:123], v[78:79], off offset:32

.LBB0_447:
	v_pk_fma_f32 v[74:75], v[210:211], v[74:75], v[170:171]
	v_pk_fma_f32 v[76:77], v[212:213], v[76:77], v[172:173]
	v_cvt_pk_bf16_f32 v74, v74, v75
	s_nop 0
	v_cvt_pk_bf16_f32 v75, v76, v77
	global_store_dwordx2 v[118:119], v[74:75], off offset:32
.LBB0_448:
	ds_read_b64 v[74:75], v0 offset:8192
	s_and_b64 vcc, exec, s[4:5]
	s_mov_b64 s[10:11], -1
	s_waitcnt lgkmcnt(0)
	v_sub_f32_e32 v71, v71, v74
	v_sub_f32_e32 v70, v70, v74
	v_sub_f32_e32 v73, v73, v74
	v_sub_f32_e32 v72, v72, v74
	v_pk_mul_f32 v[72:73], v[74:75], v[72:73] op_sel:[1,0]
	v_pk_mul_f32 v[70:71], v[74:75], v[70:71] op_sel:[1,0]
	v_pk_fma_f32 v[72:73], v[84:85], v[72:73], v[88:89]
	v_pk_fma_f32 v[70:71], v[82:83], v[70:71], v[86:87]
	v_cndmask_b32_e64 v73, v250, v73, s[8:9]
	v_cndmask_b32_e64 v72, v250, v72, s[8:9]
	v_cndmask_b32_e64 v71, v250, v71, s[8:9]
	v_cndmask_b32_e64 v70, v250, v70, s[8:9]
	s_cbranch_vccz .LBB0_558
	s_andn2_b64 vcc, exec, s[10:11]
	s_cbranch_vccz .LBB0_559

.LBB0_451:
	v_pk_fma_f32 v[70:71], v[202:203], v[70:71], v[166:167]
	v_pk_fma_f32 v[72:73], v[204:205], v[72:73], v[168:169]
	v_cvt_pk_bf16_f32 v70, v70, v71
	s_nop 0
	v_cvt_pk_bf16_f32 v71, v72, v73
	global_store_dwordx2 v[196:197], v[70:71], off offset:256

.LBB0_455:
	v_pk_fma_f32 v[66:67], v[202:203], v[66:67], v[166:167]
	v_pk_fma_f32 v[68:69], v[204:205], v[68:69], v[168:169]
	v_cvt_pk_bf16_f32 v66, v66, v67
	s_nop 0
	v_cvt_pk_bf16_f32 v67, v68, v69
	global_store_dwordx2 v[142:143], v[66:67], off offset:256

.LBB0_459:
	v_pk_fma_f32 v[62:63], v[202:203], v[62:63], v[166:167]
	v_pk_fma_f32 v[64:65], v[204:205], v[64:65], v[168:169]
	v_cvt_pk_bf16_f32 v62, v62, v63
	s_nop 0
	v_cvt_pk_bf16_f32 v63, v64, v65
	global_store_dwordx2 v[138:139], v[62:63], off offset:256

.LBB0_463:
	v_pk_fma_f32 v[58:59], v[202:203], v[58:59], v[166:167]
	v_pk_fma_f32 v[60:61], v[204:205], v[60:61], v[168:169]
	v_cvt_pk_bf16_f32 v58, v58, v59
	s_nop 0
	v_cvt_pk_bf16_f32 v59, v60, v61
	global_store_dwordx2 v[134:135], v[58:59], off offset:256

.LBB0_467:
	v_pk_fma_f32 v[54:55], v[202:203], v[54:55], v[166:167]
	v_pk_fma_f32 v[56:57], v[204:205], v[56:57], v[168:169]
	v_cvt_pk_bf16_f32 v54, v54, v55
	s_nop 0
	v_cvt_pk_bf16_f32 v55, v56, v57
	global_store_dwordx2 v[130:131], v[54:55], off offset:256

.LBB0_471:
	v_pk_fma_f32 v[50:51], v[202:203], v[50:51], v[166:167]
	v_pk_fma_f32 v[52:53], v[204:205], v[52:53], v[168:169]
	v_cvt_pk_bf16_f32 v50, v50, v51
	s_nop 0
	v_cvt_pk_bf16_f32 v51, v52, v53
	global_store_dwordx2 v[126:127], v[50:51], off offset:256

.LBB0_475:
	v_pk_fma_f32 v[46:47], v[202:203], v[46:47], v[166:167]
	v_pk_fma_f32 v[48:49], v[204:205], v[48:49], v[168:169]
	v_cvt_pk_bf16_f32 v46, v46, v47
	s_nop 0
	v_cvt_pk_bf16_f32 v47, v48, v49
	global_store_dwordx2 v[122:123], v[46:47], off offset:256

.LBB0_479:
	v_pk_fma_f32 v[42:43], v[202:203], v[42:43], v[166:167]
	v_pk_fma_f32 v[44:45], v[204:205], v[44:45], v[168:169]
	v_cvt_pk_bf16_f32 v42, v42, v43
	s_nop 0
	v_cvt_pk_bf16_f32 v43, v44, v45
	global_store_dwordx2 v[118:119], v[42:43], off offset:256
.LBB0_480:
	ds_read_b64 v[42:43], v0 offset:8192
	s_and_b64 vcc, exec, s[4:5]
	s_mov_b64 s[10:11], -1
	s_waitcnt lgkmcnt(0)
	v_sub_f32_e32 v39, v39, v42
	v_sub_f32_e32 v38, v38, v42
	v_sub_f32_e32 v41, v41, v42
	v_sub_f32_e32 v40, v40, v42
	v_pk_mul_f32 v[40:41], v[42:43], v[40:41] op_sel:[1,0]
	v_pk_mul_f32 v[38:39], v[42:43], v[38:39] op_sel:[1,0]
	v_pk_fma_f32 v[40:41], v[8:9], v[40:41], v[12:13]
	v_pk_fma_f32 v[38:39], v[6:7], v[38:39], v[10:11]
	v_cndmask_b32_e64 v41, v250, v41, s[8:9]
	v_cndmask_b32_e64 v40, v250, v40, s[8:9]
	v_cndmask_b32_e64 v39, v250, v39, s[8:9]
	v_cndmask_b32_e64 v38, v250, v38, s[8:9]
	s_cbranch_vccz .LBB0_574
	s_andn2_b64 vcc, exec, s[10:11]
	s_cbranch_vccz .LBB0_575
